# FFN-up: per-XCD rotation of the round order (XCDs stream different weight column tiles at a given time)
# speedup vs baseline: 1.1044x; 1.1044x over previous
.LBB0_1146:
	s_andn2_b64 vcc, exec, s[0:1]
	s_cbranch_vccnz .LBB0_1248
	v_readlane_b32 s0, v254, 61
	s_lshr_b32 s7, s0, 8
	v_mbcnt_lo_u32_b32 v0, -1, 0
	v_mbcnt_hi_u32_b32 v0, -1, v0
	v_readlane_b32 s0, v254, 32
	s_mul_i32 s40, s7, 44
	s_cmp_lt_i32 s66, s40
	v_mov_b32_e32 v0, s0
	ds_read2_b64 v[0:3], v0 offset1:1
	s_cselect_b64 s[0:1], -1, 0
	s_lshr_b32 s2, s40, 3
	v_mbcnt_lo_u32_b32 v8, -1, 0
	v_mbcnt_hi_u32_b32 v8, -1, v8
	v_writelane_b32 v254, s2, 63
	s_waitcnt lgkmcnt(0)
	v_readfirstlane_b32 s12, v0
	v_add_u32_e32 v0, s77, v8
	s_cmp_ge_i32 s66, s40
	v_readfirstlane_b32 s13, v1
	v_readfirstlane_b32 s3, v2
	v_readfirstlane_b32 s6, v3
	v_readfirstlane_b32 s2, v0
	s_cbranch_scc1 .LBB0_1149
	v_readlane_b32 s4, v253, 4
	v_readlane_b32 s5, v254, 63
	s_add_i32 s4, s5, s4
	v_readlane_b32 s5, v253, 3
	s_mul_i32 s4, s4, s5
	v_readlane_b32 s5, v252, 58
	s_add_i32 s4, s4, s5
	s_and_b32 s8, s66, 7
	s_cmp_gt_u32 s8, 4
	s_cselect_b32 s9, 5, 0
	s_sub_i32 s8, s8, s9
	s_lshl_b32 s8, s8, 5
	s_add_i32 s4, s4, s8
	s_mul_hi_i32 s5, s4, 0x2e8ba2e9
	s_lshr_b32 s8, s5, 31
	s_ashr_i32 s5, s5, 6
	s_add_i32 s5, s5, s8
	s_lshl_b32 s8, s5, 3
	s_sub_i32 s9, s7, s8
	s_min_i32 s9, s9, 8
	s_abs_i32 s10, s9
	v_cvt_f32_u32_e32 v1, s10
	s_sub_i32 s14, 0, s10
	s_mulk_i32 s5, 0x160
	s_sub_i32 s4, s4, s5
	v_rcp_iflag_f32_e32 v1, v1
	s_abs_i32 s5, s4
	s_xor_b32 s11, s4, s9
	s_ashr_i32 s11, s11, 31
	v_mul_f32_e32 v1, 0x4f7ffffe, v1
	v_cvt_u32_f32_e32 v1, v1
	s_nop 0
	v_readfirstlane_b32 s15, v1
	s_mul_i32 s14, s14, s15
	s_mul_hi_u32 s14, s15, s14
	s_add_i32 s15, s15, s14
	s_mul_hi_u32 s14, s5, s15
	s_mul_i32 s15, s14, s10
	s_sub_i32 s5, s5, s15
	s_add_i32 s17, s14, 1
	s_sub_i32 s15, s5, s10
	s_cmp_ge_u32 s5, s10
	s_cselect_b32 s14, s17, s14
	s_cselect_b32 s5, s15, s5
	s_add_i32 s15, s14, 1
	s_cmp_ge_u32 s5, s10
	s_cselect_b32 s5, s15, s14
	s_xor_b32 s5, s5, s11
	s_sub_i32 s60, s5, s11
	s_mul_i32 s5, s60, s9
	s_sub_i32 s4, s4, s5
	s_add_i32 s22, s8, s4

.LBB0_1155:
	s_add_i32 s66, s66, 1
	s_and_b32 s58, s84, 7
	s_add_i32 s58, s58, s66
	s_cmp_gt_u32 s58, 4
	s_cselect_b32 s59, 5, 0
	s_sub_i32 s58, s58, s59
	s_cmp_gt_u32 s58, 4
	s_cselect_b32 s59, 5, 0
	s_sub_i32 s58, s58, s59
	s_cmp_lt_u32 s66, 5
	s_cselect_b32 s58, s58, s66
	v_readlane_b32 s6, v254, 58
	s_mul_i32 s2, s58, s82
	s_mul_hi_u32 s3, s58, s6
	s_add_i32 s3, s3, s2
	s_mul_i32 s2, s58, s6
	s_mov_b64 s[58:59], s[84:85]
	s_add_u32 s74, s2, s58
	s_addc_u32 s75, s3, s59
	v_mov_b64_e32 v[0:1], s[40:41]
	v_cmp_ge_i64_e32 vcc, s[74:75], v[0:1]
	v_cmp_lt_i64_e64 s[58:59], s[74:75], v[0:1]
	s_cbranch_vccnz .LBB0_1157
	s_ashr_i32 s2, s74, 31
	s_lshr_b32 s2, s2, 29
	s_add_i32 s2, s74, s2
	s_ashr_i32 s3, s2, 3
	s_and_b32 s2, s2, -8
	s_sub_i32 s2, s74, s2
	s_lshr_b32 s6, s2, 31
	v_readlane_b32 s23, v254, 63
	s_add_i32 s6, s23, s6
	s_mul_i32 s2, s6, s2
	s_add_i32 s2, s2, s3
	s_mul_hi_i32 s3, s2, 0x2e8ba2e9
	s_lshr_b32 s6, s3, 31
	s_ashr_i32 s3, s3, 6
	s_add_i32 s3, s3, s6
	s_lshl_b32 s6, s3, 3
	s_sub_i32 s23, s7, s6
	s_min_i32 s23, s23, 8
	s_abs_i32 s61, s23
	v_cvt_f32_u32_e32 v0, s61
	s_sub_i32 s75, 0, s61
	s_mulk_i32 s3, 0x160
	s_sub_i32 s2, s2, s3
	v_rcp_iflag_f32_e32 v0, v0
	s_abs_i32 s3, s2
	s_xor_b32 s74, s2, s23
	s_ashr_i32 s74, s74, 31
	v_mul_f32_e32 v0, 0x4f7ffffe, v0
	v_cvt_u32_f32_e32 v0, v0
	s_nop 0
	v_readfirstlane_b32 s82, v0
	s_mul_i32 s75, s75, s82
	s_mul_hi_u32 s75, s82, s75
	s_add_i32 s82, s82, s75
	s_mul_hi_u32 s75, s3, s82
	s_mul_i32 s82, s75, s61
	s_sub_i32 s3, s3, s82
	s_add_i32 s83, s75, 1
	s_sub_i32 s82, s3, s61
	s_cmp_ge_u32 s3, s61
	s_cselect_b32 s75, s83, s75
	s_cselect_b32 s3, s82, s3
	s_add_i32 s82, s75, 1
	s_cmp_ge_u32 s3, s61
	s_cselect_b32 s3, s82, s75
	s_xor_b32 s3, s3, s74
	s_sub_i32 s92, s3, s74
	s_mul_i32 s3, s92, s23
	s_sub_i32 s2, s2, s3
	s_add_i32 s90, s2, s6
